# seam 1 also XCD-local: P1 row blocks remapped to the consuming XCD, BVIN stored write-through
# speedup vs baseline: 1.0558x; 1.0062x over previous
.LBB0_95:
	s_or_b64 exec, exec, s[4:5]
	s_waitcnt lgkmcnt(0)
	s_barrier
	s_mov_b64 s[4:5], exec
	v_readlane_b32 s6, v255, 1
	v_readlane_b32 s7, v255, 2
	s_and_b64 s[6:7], s[4:5], s[6:7]
	s_mov_b64 exec, s[6:7]
	s_cbranch_execz .LBB0_107
	s_and_b32 s3, s34, 7
	s_cmp_eq_u32 s3, 0
	s_cselect_b64 s[6:7], -1, 0
	s_cmp_lt_u32 s33, 8
	s_cselect_b64 s[8:9], -1, 0
	s_and_b64 s[6:7], s[6:7], s[8:9]
	s_andn2_b64 vcc, exec, s[6:7]
	v_mov_b32_e32 v0, s80
	s_cbranch_vccnz .LBB0_106
	v_mov_b32_e32 v1, 0xfc00000
	global_load_dword v0, v1, s[30:31] offset:1024 sc1
	s_ashr_i32 s3, s34, 31
	s_lshr_b32 s3, s3, 29
	s_add_i32 s3, s34, s3
	s_ashr_i32 s3, s3, 3
	s_waitcnt vmcnt(0)
	v_cmp_ne_u32_e32 vcc, s3, v0
	v_mov_b32_e32 v0, s80
	s_cbranch_vccnz .LBB0_106
	global_load_dword v0, v1, s[30:31] offset:1280 sc1
	s_waitcnt vmcnt(0)
	v_cmp_ne_u32_e32 vcc, s3, v0
	v_mov_b32_e32 v0, s80
	s_cbranch_vccnz .LBB0_106
	v_mov_b32_e32 v1, 0xfc00000
	global_load_dword v0, v1, s[30:31] offset:1536 sc1
	s_waitcnt vmcnt(0)
	v_cmp_ne_u32_e32 vcc, s3, v0
	v_mov_b32_e32 v0, s80
	s_cbranch_vccnz .LBB0_106
	global_load_dword v0, v1, s[30:31] offset:1792 sc1
	s_waitcnt vmcnt(0)
	v_cmp_ne_u32_e32 vcc, s3, v0
	v_mov_b32_e32 v0, s80
	s_cbranch_vccnz .LBB0_106
	v_mov_b32_e32 v1, 0xfc00000
	global_load_dword v0, v1, s[30:31] offset:2048 sc1
	s_waitcnt vmcnt(0)
	v_cmp_ne_u32_e32 vcc, s3, v0
	v_mov_b32_e32 v0, s80
	s_cbranch_vccnz .LBB0_106
	global_load_dword v0, v1, s[30:31] offset:2304 sc1
	s_waitcnt vmcnt(0)
	v_cmp_ne_u32_e32 vcc, s3, v0
	v_mov_b32_e32 v0, s80
	s_cbranch_vccnz .LBB0_106
	v_mov_b32_e32 v1, 0xfc00000
	global_load_dword v0, v1, s[30:31] offset:2560 sc1
	s_waitcnt vmcnt(0)
	v_cmp_ne_u32_e32 vcc, s3, v0
	v_mov_b32_e32 v0, s80
	s_cbranch_vccnz .LBB0_106
	global_load_dword v0, v1, s[30:31] offset:2816 sc1
	s_waitcnt vmcnt(0)
	v_cmp_ne_u32_e32 vcc, s3, v0
	v_mov_b32_e32 v0, s80
	s_cbranch_vccnz .LBB0_106
	s_add_i32 s3, 0, 0x20048
	v_mov_b32_e32 v0, s3
	ds_read_b32 v0, v0
	s_waitcnt lgkmcnt(0)
	v_lshlrev_b32_e32 v0, 3, v0
	v_or_b32_e32 v0, s33, v0
	s_cmp_lg_u32 s34, 0x100
	s_cbranch_scc1 .Lxl_noflag
	v_mov_b32_e32 v1, 0x20050
	ds_write_b32 v1, v1
.Lxl_noflag:
.LBB0_106:
	s_add_i32 s3, 0, 0x2004c
	v_mov_b32_e32 v1, s3
	ds_write_b32 v1, v0

.LBB0_108:
	s_cmp_lt_i32 s68, 2
	s_cselect_b64 s[4:5], -1, 0
	s_add_u32 s40, s30, 0x3400000
	s_addc_u32 s41, s31, 0
	s_and_b64 s[4:5], s[4:5], s[0:1]
	s_add_i32 s44, s23, s2
	s_andn2_b64 vcc, exec, s[4:5]
	s_waitcnt lgkmcnt(0)
	v_readfirstlane_b32 s38, v0
	s_cbranch_vccnz .LBB0_125
	s_and_b32 s66, s38, 7
	s_lshl_b32 s66, s66, 5
	s_lshr_b32 s3, s38, 3
	s_add_i32 s66, s66, s3
	s_cmp_eq_u32 s34, 0x100
	s_cselect_b32 s66, s66, s80
	s_cmpk_gt_i32 s66, 0xff
	s_cbranch_scc1 .LBB0_120
	v_mbcnt_lo_u32_b32 v1, -1, 0
	v_mbcnt_hi_u32_b32 v1, -1, v1
	v_and_b32_e32 v2, 64, v1
	v_mov_b32_e32 v3, 0
	v_add_u32_e32 v5, 64, v2
	v_lshlrev_b32_e32 v2, 3, v222
	v_lshl_add_u64 v[96:97], s[40:41], 0, v[2:3]
	v_lshlrev_b32_e32 v2, 4, v222
	v_lshl_add_u64 v[98:99], s[36:37], 0, v[2:3]
	v_xor_b32_e32 v3, 1, v1
	v_cmp_lt_i32_e32 vcc, v3, v5
	v_lshlrev_b32_e32 v0, 2, v222
	v_or_b32_e32 v2, 0x100, v0
	v_cndmask_b32_e32 v3, v1, v3, vcc
	v_lshlrev_b32_e32 v104, 2, v3
	v_xor_b32_e32 v3, 2, v1
	v_cmp_lt_i32_e32 vcc, v3, v5
	v_or_b32_e32 v4, 0x200, v0
	v_or_b32_e32 v6, 0x300, v0
	v_cndmask_b32_e32 v3, v1, v3, vcc
	v_lshlrev_b32_e32 v105, 2, v3
	v_xor_b32_e32 v3, 4, v1
	v_cmp_lt_i32_e32 vcc, v3, v5
	s_lshl_b32 s2, s23, 3
	s_mov_b32 s7, 0
	v_cndmask_b32_e32 v3, v1, v3, vcc
	v_lshlrev_b32_e32 v106, 2, v3
	v_xor_b32_e32 v3, 8, v1
	v_cmp_lt_i32_e32 vcc, v3, v5
	s_lshl_b32 s3, s66, 6
	s_lshl_b32 s39, s34, 6
	v_cndmask_b32_e32 v3, v1, v3, vcc
	v_lshlrev_b32_e32 v107, 2, v3
	v_xor_b32_e32 v3, 16, v1
	v_cmp_lt_i32_e32 vcc, v3, v5
	v_lshlrev_b32_e32 v110, 2, v0
	v_lshlrev_b32_e32 v111, 2, v2
	v_cndmask_b32_e32 v3, v1, v3, vcc
	v_lshlrev_b32_e32 v108, 2, v3
	v_xor_b32_e32 v3, 32, v1
	v_cmp_lt_i32_e32 vcc, v3, v5
	v_lshlrev_b32_e32 v112, 2, v4
	v_lshlrev_b32_e32 v113, 2, v6
	v_cndmask_b32_e32 v1, v1, v3, vcc
	v_lshlrev_b32_e32 v109, 2, v1
	v_mov_b32_e32 v114, 0x358637bd
	s_mov_b32 s45, 0xf800000
	v_mov_b32_e32 v115, 0x260
	s_branch .LBB0_112

.LBB0_123:
	s_waitcnt lgkmcnt(3)
	v_lshl_add_u64 v[98:99], s[30:31], 0, v[80:81]
	v_add_co_u32_e32 v94, vcc, 0x2200000, v98
	s_nop 1
	v_addc_co_u32_e32 v95, vcc, 0, v99, vcc
	global_load_dwordx4 v[94:97], v[94:95], off
	v_lshl_add_u64 v[98:99], v[98:99], 0, s[60:61]
	s_waitcnt lgkmcnt(1)
	global_load_dwordx4 v[98:101], v[98:99], off offset:16
	s_waitcnt vmcnt(1)
	v_lshlrev_b32_e32 v93, 16, v94
	v_and_b32_e32 v94, 0xffff0000, v94
	v_fma_f32 v109, v8, v93, 0
	v_fma_f32 v110, v24, v93, 0
	v_fma_f32 v111, v40, v93, 0
	v_fma_f32 v112, v56, v93, 0
	v_fma_f32 v93, v72, v93, 0
	s_waitcnt lgkmcnt(0)
	v_lshlrev_b32_e32 v102, 16, v95
	v_fmac_f32_e32 v109, v9, v94
	v_fmac_f32_e32 v110, v25, v94
	v_fmac_f32_e32 v111, v41, v94
	v_fmac_f32_e32 v112, v57, v94
	v_fmac_f32_e32 v93, v73, v94
	v_and_b32_e32 v95, 0xffff0000, v95
	v_fmac_f32_e32 v109, v10, v102
	v_fmac_f32_e32 v110, v26, v102
	v_fmac_f32_e32 v111, v42, v102
	v_fmac_f32_e32 v112, v58, v102
	v_fmac_f32_e32 v93, v74, v102
	v_lshlrev_b32_e32 v103, 16, v96
	v_fmac_f32_e32 v109, v11, v95
	v_fmac_f32_e32 v110, v27, v95
	v_fmac_f32_e32 v111, v43, v95
	v_fmac_f32_e32 v112, v59, v95
	v_fmac_f32_e32 v93, v75, v95
	v_and_b32_e32 v96, 0xffff0000, v96
	v_fmac_f32_e32 v109, v0, v103
	v_fmac_f32_e32 v110, v16, v103
	v_fmac_f32_e32 v111, v32, v103
	v_fmac_f32_e32 v112, v48, v103
	v_fmac_f32_e32 v93, v64, v103
	v_lshlrev_b32_e32 v104, 16, v97
	v_fmac_f32_e32 v109, v1, v96
	v_fmac_f32_e32 v110, v17, v96
	v_fmac_f32_e32 v111, v33, v96
	v_fmac_f32_e32 v112, v49, v96
	v_fmac_f32_e32 v93, v65, v96
	v_and_b32_e32 v97, 0xffff0000, v97
	v_fmac_f32_e32 v109, v2, v104
	v_fmac_f32_e32 v110, v18, v104
	v_fmac_f32_e32 v111, v34, v104
	v_fmac_f32_e32 v112, v50, v104
	v_fmac_f32_e32 v93, v66, v104
	s_waitcnt vmcnt(0)
	v_lshlrev_b32_e32 v105, 16, v98
	v_fmac_f32_e32 v109, v3, v97
	v_fmac_f32_e32 v110, v19, v97
	v_fmac_f32_e32 v111, v35, v97
	v_fmac_f32_e32 v112, v51, v97
	v_fmac_f32_e32 v93, v67, v97
	v_and_b32_e32 v98, 0xffff0000, v98
	v_fmac_f32_e32 v109, v4, v105
	v_fmac_f32_e32 v110, v20, v105
	v_fmac_f32_e32 v111, v36, v105
	v_fmac_f32_e32 v112, v52, v105
	v_fmac_f32_e32 v93, v68, v105
	v_lshlrev_b32_e32 v106, 16, v99
	v_fmac_f32_e32 v109, v5, v98
	v_fmac_f32_e32 v110, v21, v98
	v_fmac_f32_e32 v111, v37, v98
	v_fmac_f32_e32 v112, v53, v98
	v_fmac_f32_e32 v93, v69, v98
	v_and_b32_e32 v99, 0xffff0000, v99
	v_fmac_f32_e32 v109, v6, v106
	v_fmac_f32_e32 v110, v22, v106
	v_fmac_f32_e32 v111, v38, v106
	v_fmac_f32_e32 v112, v54, v106
	v_fmac_f32_e32 v93, v70, v106
	v_lshlrev_b32_e32 v107, 16, v100
	v_fmac_f32_e32 v109, v7, v99
	v_fmac_f32_e32 v110, v23, v99
	v_fmac_f32_e32 v111, v39, v99
	v_fmac_f32_e32 v112, v55, v99
	v_fmac_f32_e32 v93, v71, v99
	v_and_b32_e32 v100, 0xffff0000, v100
	v_fmac_f32_e32 v109, v12, v107
	v_fmac_f32_e32 v110, v28, v107
	v_fmac_f32_e32 v111, v44, v107
	v_fmac_f32_e32 v112, v60, v107
	v_fmac_f32_e32 v93, v76, v107
	v_lshlrev_b32_e32 v108, 16, v101
	v_fmac_f32_e32 v109, v13, v100
	v_fmac_f32_e32 v110, v29, v100
	v_fmac_f32_e32 v111, v45, v100
	v_fmac_f32_e32 v112, v61, v100
	v_fmac_f32_e32 v93, v77, v100
	v_and_b32_e32 v101, 0xffff0000, v101
	v_fmac_f32_e32 v109, v14, v108
	v_fmac_f32_e32 v110, v30, v108
	v_fmac_f32_e32 v111, v46, v108
	v_fmac_f32_e32 v112, v62, v108
	v_fmac_f32_e32 v93, v78, v108
	v_fmac_f32_e32 v109, v15, v101
	v_fmac_f32_e32 v110, v31, v101
	v_fmac_f32_e32 v111, v47, v101
	v_fmac_f32_e32 v112, v63, v101
	v_fmac_f32_e32 v93, v79, v101
	ds_bpermute_b32 v94, v82, v109
	ds_bpermute_b32 v95, v82, v110
	ds_bpermute_b32 v96, v82, v111
	ds_bpermute_b32 v97, v82, v112
	ds_bpermute_b32 v98, v82, v93
	s_waitcnt lgkmcnt(4)
	v_add_f32_e32 v94, v109, v94
	s_waitcnt lgkmcnt(3)
	v_add_f32_e32 v95, v110, v95
	s_waitcnt lgkmcnt(2)
	v_add_f32_e32 v96, v111, v96
	s_waitcnt lgkmcnt(1)
	v_add_f32_e32 v97, v112, v97
	s_waitcnt lgkmcnt(0)
	v_add_f32_e32 v93, v93, v98
	ds_bpermute_b32 v98, v83, v94
	ds_bpermute_b32 v99, v83, v95
	ds_bpermute_b32 v100, v83, v96
	ds_bpermute_b32 v101, v83, v97
	ds_bpermute_b32 v102, v83, v93
	s_waitcnt lgkmcnt(4)
	v_add_f32_e32 v94, v94, v98
	s_waitcnt lgkmcnt(3)
	v_add_f32_e32 v95, v95, v99
	s_waitcnt lgkmcnt(2)
	v_add_f32_e32 v96, v96, v100
	s_waitcnt lgkmcnt(1)
	v_add_f32_e32 v97, v97, v101
	s_waitcnt lgkmcnt(0)
	v_add_f32_e32 v93, v93, v102
	ds_bpermute_b32 v98, v84, v94
	ds_bpermute_b32 v99, v84, v95
	ds_bpermute_b32 v100, v84, v96
	ds_bpermute_b32 v101, v84, v97
	ds_bpermute_b32 v102, v84, v93
	s_waitcnt lgkmcnt(4)
	v_add_f32_e32 v94, v94, v98
	s_waitcnt lgkmcnt(3)
	v_add_f32_e32 v95, v95, v99
	s_waitcnt lgkmcnt(2)
	v_add_f32_e32 v96, v96, v100
	s_waitcnt lgkmcnt(1)
	v_add_f32_e32 v97, v97, v101
	s_waitcnt lgkmcnt(0)
	v_add_f32_e32 v93, v93, v102
	ds_bpermute_b32 v98, v85, v94
	ds_bpermute_b32 v99, v85, v95
	ds_bpermute_b32 v100, v85, v96
	ds_bpermute_b32 v101, v85, v97
	ds_bpermute_b32 v102, v85, v93
	s_waitcnt lgkmcnt(4)
	v_add_f32_e32 v94, v94, v98
	s_waitcnt lgkmcnt(3)
	v_add_f32_e32 v95, v95, v99
	s_waitcnt lgkmcnt(2)
	v_add_f32_e32 v96, v96, v100
	s_waitcnt lgkmcnt(1)
	v_add_f32_e32 v97, v97, v101
	s_waitcnt lgkmcnt(0)
	v_add_f32_e32 v98, v93, v102
	ds_bpermute_b32 v93, v86, v94
	ds_bpermute_b32 v99, v86, v95
	ds_bpermute_b32 v100, v86, v96
	ds_bpermute_b32 v101, v86, v97
	ds_bpermute_b32 v102, v86, v98
	s_waitcnt lgkmcnt(4)
	v_add_f32_e32 v93, v94, v93
	s_waitcnt lgkmcnt(3)
	v_add_f32_e32 v94, v95, v99
	s_waitcnt lgkmcnt(2)
	v_add_f32_e32 v95, v96, v100
	s_waitcnt lgkmcnt(1)
	v_add_f32_e32 v97, v97, v101
	s_waitcnt lgkmcnt(0)
	v_add_f32_e32 v99, v98, v102
	ds_bpermute_b32 v96, v87, v93
	ds_bpermute_b32 v98, v87, v94
	ds_bpermute_b32 v100, v87, v95
	ds_bpermute_b32 v101, v87, v97
	ds_bpermute_b32 v102, v87, v99
	s_and_saveexec_b64 s[10:11], s[0:1]
	s_cbranch_execz .LBB0_122
	s_add_u32 s62, s30, s6
	s_waitcnt lgkmcnt(4)
	v_add_f32_e32 v93, v93, v96
	s_addc_u32 s63, s31, s7
	s_waitcnt lgkmcnt(0)
	v_add_f32_e32 v99, v99, v102
	v_add_f32_e32 v97, v97, v101
	v_add_f32_e32 v95, v95, v100
	v_add_f32_e32 v94, v94, v98
	global_store_dword v88, v93, s[62:63] sc0 sc1
	global_store_dword v89, v94, s[62:63] sc0 sc1
	global_store_dword v90, v95, s[62:63] sc0 sc1
	global_store_dword v91, v97, s[62:63] sc0 sc1
	global_store_dword v92, v99, s[62:63] sc0 sc1
	s_branch .LBB0_122
.LBB0_125:
	s_cmp_gt_i32 s69, 2
	s_cselect_b64 s[0:1], -1, 0
	s_and_b64 s[2:3], s[4:5], s[0:1]
	s_andn2_b64 vcc, exec, s[2:3]
	s_cbranch_vccnz .LBB0_179
	s_waitcnt vmcnt(0)
	s_waitcnt lgkmcnt(0)
	s_barrier
	v_mov_b32_e32 v0, 0x20040
	ds_read_b32 v2, v0
	ds_read_b32 v3, v0 offset:16
	ds_read_b32 v5, v0 offset:8
	s_lshl_b32 s2, s33, 7
	s_add_u32 s2, s2, 0x3600
	v_lshl_add_u32 v0, v199, 2, s2
	v_mov_b32_e32 v6, 1
	s_waitcnt lgkmcnt(0)
	v_cmp_eq_u32_e32 vcc, 0, v3
	s_cbranch_vccnz .Lxl_orig_1
	v_cmp_lt_u32_e32 vcc, 32, v2
	s_cbranch_vccnz .Lxl_orig_1
	v_lshl_add_u32 v1, v5, 2, s2
	v_cmp_lt_u32_e32 vcc, v199, v2
	s_and_saveexec_b64 s[4:5], vcc
	s_cbranch_execz .LBB0_178
	v_cmp_eq_u32_e32 vcc, 0, v199
	s_and_saveexec_b64 s[2:3], vcc
	global_store_dword v1, v6, s[92:93]
	s_mov_b64 exec, s[2:3]
	buffer_inv sc1
	s_mov_b32 s2, 0x20000

.Lxl_orig_1:
	s_mov_b64 s[4:5], exec
	v_readlane_b32 s2, v255, 1
	v_readlane_b32 s3, v255, 2
	s_and_b64 s[2:3], s[4:5], s[2:3]
	s_mov_b64 exec, s[2:3]
	s_cbranch_execz .LBB0_178
	s_add_i32 s2, 0, 0x20040
	v_mov_b32_e32 v0, s2
	s_waitcnt vmcnt(0) expcnt(0) lgkmcnt(0)
	ds_read_b32 v2, v0
	s_add_i32 s2, 0, 0x20044
	v_mov_b32_e32 v0, s2
	ds_read_b32 v0, v0
	s_waitcnt lgkmcnt(1)
	v_cmp_ne_u32_e32 vcc, 0, v2
	s_cbranch_vccnz .LBB0_142
	s_add_u32 s6, s30, 0xfc00200
	s_addc_u32 s7, s31, 0
	s_add_u32 s8, s30, 0xfc00400
	s_addc_u32 s9, s31, 0
	s_add_u32 s36, s30, 0xfc00500
	s_addc_u32 s37, s31, 0
	s_add_u32 s60, s30, 0xfc00600
	s_addc_u32 s61, s31, 0
	s_add_u32 s62, s30, 0xfc00700
	s_addc_u32 s63, s31, 0
	s_add_u32 s64, s30, 0xfc00800
	s_addc_u32 s65, s31, 0
	s_add_u32 s66, s30, 0xfc00900
	s_addc_u32 s67, s31, 0
	s_add_u32 s76, s30, 0xfc00a00
	s_addc_u32 s77, s31, 0
	s_add_u32 s78, s30, 0xfc00b00
	s_addc_u32 s79, s31, 0
	s_mov_b32 s14, s80
	s_add_u32 s80, s30, 0xfc00c00
	s_addc_u32 s81, s31, 0
	s_add_u32 s82, s30, 0xfc00d00
	s_addc_u32 s83, s31, 0
	s_add_u32 s84, s30, 0xfc00e00
	s_addc_u32 s85, s31, 0
	s_add_u32 s86, s30, 0xfc00f00
	s_addc_u32 s87, s31, 0
	s_add_u32 s88, s30, 0xfc01000
	s_addc_u32 s89, s31, 0
	s_add_u32 s90, s30, 0xfc01100
	s_addc_u32 s91, s31, 0
	s_mov_b64 s[12:13], s[92:93]
	s_add_u32 s92, s30, 0xfc01200
	v_readlane_b32 s2, v255, 0
	s_addc_u32 s93, s31, 0
	s_mul_i32 s2, s35, s2
	s_add_u32 s94, s30, 0xfc01300
	s_mul_i32 s2, s2, s34
	s_addc_u32 s95, s31, 0
	s_mov_b32 s3, 1
	v_mov_b32_e32 v16, 0
	s_branch .LBB0_130

.LBB0_262:
	s_cmp_gt_i32 s69, 3
	s_cselect_b64 s[0:1], -1, 0
	s_and_b64 s[2:3], s[4:5], s[0:1]
	s_andn2_b64 vcc, exec, s[2:3]
	s_cbranch_vccnz .LBB0_316
	s_waitcnt vmcnt(0)
	s_waitcnt vmcnt(0) lgkmcnt(0)
	s_barrier
	v_mov_b32_e32 v0, 0x20040
	ds_read_b32 v2, v0
	ds_read_b32 v3, v0 offset:16
	ds_read_b32 v5, v0 offset:8
	s_lshl_b32 s2, s33, 7
	s_add_u32 s2, s2, 0x3600
	v_lshl_add_u32 v0, v199, 2, s2
	v_mov_b32_e32 v6, 2
	s_waitcnt lgkmcnt(0)
	v_cmp_eq_u32_e32 vcc, 0, v3
	s_cbranch_vccnz .Lxl_orig_2
	v_cmp_lt_u32_e32 vcc, 32, v2
	s_cbranch_vccnz .Lxl_orig_2
	v_lshl_add_u32 v1, v5, 2, s2
	v_cmp_lt_u32_e32 vcc, v199, v2
	s_and_saveexec_b64 s[4:5], vcc
	s_cbranch_execz .LBB0_315
	v_cmp_eq_u32_e32 vcc, 0, v199
	s_and_saveexec_b64 s[2:3], vcc
	global_store_dword v1, v6, s[92:93]
	s_mov_b64 exec, s[2:3]
	buffer_inv sc1
	s_mov_b32 s2, 0x20000
.Lxl_poll_2:
	global_load_dword v4, v0, s[92:93] sc1
	s_waitcnt vmcnt(0)
	v_cmp_gt_u32_e32 vcc, 2, v4
	s_cbranch_vccz .LBB0_315
	s_sleep 1
	s_sub_u32 s2, s2, 1
	s_cmp_lg_u32 s2, 0
	s_cbranch_scc1 .Lxl_poll_2
	s_branch .LBB0_315
.Lxl_orig_2:
	s_mov_b64 s[4:5], exec
	v_readlane_b32 s2, v255, 1
	v_readlane_b32 s3, v255, 2
	s_and_b64 s[2:3], s[4:5], s[2:3]
	s_mov_b64 exec, s[2:3]
	s_cbranch_execz .LBB0_315
	s_add_i32 s2, 0, 0x20040
	v_mov_b32_e32 v0, s2
	s_waitcnt vmcnt(0) expcnt(0) lgkmcnt(0)
	ds_read_b32 v2, v0
	s_add_i32 s2, 0, 0x20044
	v_mov_b32_e32 v0, s2
	ds_read_b32 v0, v0
	s_waitcnt lgkmcnt(1)
	v_cmp_ne_u32_e32 vcc, 0, v2
	s_cbranch_vccnz .LBB0_279
	s_add_u32 s6, s30, 0xfc00200
	s_addc_u32 s7, s31, 0
	s_add_u32 s8, s30, 0xfc00400
	s_addc_u32 s9, s31, 0
	s_add_u32 s12, s30, 0xfc00500
	s_addc_u32 s13, s31, 0
	s_add_u32 s16, s30, 0xfc00600
	s_addc_u32 s17, s31, 0
	s_add_u32 s18, s30, 0xfc00700
	s_addc_u32 s19, s31, 0
	s_add_u32 s20, s30, 0xfc00800
	s_addc_u32 s21, s31, 0
	s_add_u32 s24, s30, 0xfc00900
	s_addc_u32 s25, s31, 0
	s_add_u32 s26, s30, 0xfc00a00
	s_addc_u32 s27, s31, 0
	s_add_u32 s50, s30, 0xfc00b00
	s_addc_u32 s51, s31, 0
	s_add_u32 s56, s30, 0xfc00c00
	s_addc_u32 s57, s31, 0
	s_add_u32 s58, s30, 0xfc00d00
	s_addc_u32 s59, s31, 0
	s_add_u32 s60, s30, 0xfc00e00
	s_addc_u32 s61, s31, 0
	s_add_u32 s62, s30, 0xfc00f00
	s_addc_u32 s63, s31, 0
	s_add_u32 s64, s30, 0xfc01000
	s_addc_u32 s65, s31, 0
	s_add_u32 s66, s30, 0xfc01100
	s_addc_u32 s67, s31, 0
	s_add_u32 s76, s30, 0xfc01200
	v_readlane_b32 s2, v255, 0
	s_addc_u32 s77, s31, 0
	s_mul_i32 s2, s35, s2
	s_add_u32 s78, s30, 0xfc01300
	s_mov_b32 s22, s80
	s_mov_b64 s[14:15], s[92:93]
	s_mul_i32 s2, s2, s34
	s_addc_u32 s79, s31, 0
	s_mov_b32 s3, 1
	v_mov_b32_e32 v16, 0
	s_branch .LBB0_267

.LBB0_363:
	s_cmp_gt_i32 s69, 4
	s_cselect_b64 s[0:1], -1, 0
	s_and_b64 s[2:3], s[8:9], s[0:1]
	s_andn2_b64 vcc, exec, s[2:3]
	s_cbranch_vccnz .LBB0_417
	s_waitcnt vmcnt(0)
	s_waitcnt vmcnt(0) lgkmcnt(0)
	s_barrier
	v_mov_b32_e32 v0, 0x20040
	ds_read_b32 v2, v0
	ds_read_b32 v3, v0 offset:16
	ds_read_b32 v5, v0 offset:8
	s_lshl_b32 s2, s33, 7
	s_add_u32 s2, s2, 0x3600
	v_lshl_add_u32 v0, v199, 2, s2
	v_mov_b32_e32 v6, 3
	s_waitcnt lgkmcnt(0)
	v_cmp_eq_u32_e32 vcc, 0, v3
	s_cbranch_vccnz .Lxl_orig_3
	v_cmp_lt_u32_e32 vcc, 32, v2
	s_cbranch_vccnz .Lxl_orig_3
	v_lshl_add_u32 v1, v5, 2, s2
	v_cmp_lt_u32_e32 vcc, v199, v2
	s_and_saveexec_b64 s[4:5], vcc
	s_cbranch_execz .LBB0_416
	v_cmp_eq_u32_e32 vcc, 0, v199
	s_and_saveexec_b64 s[2:3], vcc
	global_store_dword v1, v6, s[92:93]
	s_mov_b64 exec, s[2:3]
	buffer_inv sc1
	s_mov_b32 s2, 0x20000
.Lxl_poll_3:
	global_load_dword v4, v0, s[92:93] sc1
	s_waitcnt vmcnt(0)
	v_cmp_gt_u32_e32 vcc, 3, v4
	s_cbranch_vccz .LBB0_416
	s_sleep 1
	s_sub_u32 s2, s2, 1
	s_cmp_lg_u32 s2, 0
	s_cbranch_scc1 .Lxl_poll_3
	s_branch .LBB0_416

.LBB0_1502:
	s_cmp_gt_i32 s69, 7
	s_cselect_b64 s[2:3], -1, 0
	s_and_b64 s[0:1], s[0:1], s[2:3]
	s_andn2_b64 vcc, exec, s[0:1]
	s_cbranch_vccnz .LBB0_1556
	s_waitcnt vmcnt(0)
	s_waitcnt vmcnt(0) lgkmcnt(0)
	s_barrier
	v_mov_b32_e32 v0, 0x20040
	ds_read_b32 v2, v0
	ds_read_b32 v3, v0 offset:16
	ds_read_b32 v5, v0 offset:8
	s_lshl_b32 s4, s33, 7
	s_add_u32 s4, s4, 0x3600
	v_lshl_add_u32 v0, v199, 2, s4
	v_mov_b32_e32 v6, 4
	s_waitcnt lgkmcnt(0)
	v_cmp_eq_u32_e32 vcc, 0, v3
	s_cbranch_vccnz .Lxl_orig_6
	v_cmp_lt_u32_e32 vcc, 32, v2
	s_cbranch_vccnz .Lxl_orig_6
	v_lshl_add_u32 v1, v5, 2, s4
	v_cmp_lt_u32_e32 vcc, v199, v2
	s_and_saveexec_b64 s[0:1], vcc
	s_cbranch_execz .LBB0_1555
	v_cmp_eq_u32_e32 vcc, 0, v199
	s_and_saveexec_b64 s[4:5], vcc
	global_store_dword v1, v6, s[92:93]
	s_mov_b64 exec, s[4:5]
	buffer_inv sc1
	s_mov_b32 s4, 0x20000
.Lxl_poll_6:
	global_load_dword v4, v0, s[92:93] sc1
	s_waitcnt vmcnt(0)
	v_cmp_gt_u32_e32 vcc, 4, v4
	s_cbranch_vccz .LBB0_1555
	s_sleep 1
	s_sub_u32 s4, s4, 1
	s_cmp_lg_u32 s4, 0
	s_cbranch_scc1 .Lxl_poll_6
	s_branch .LBB0_1555
.Lxl_orig_6:
	s_mov_b64 s[0:1], exec
	v_readlane_b32 s4, v255, 1
	v_readlane_b32 s5, v255, 2
	s_and_b64 s[4:5], s[0:1], s[4:5]
	s_mov_b64 exec, s[4:5]
	s_cbranch_execz .LBB0_1555
	s_add_i32 s4, 0, 0x20040
	v_mov_b32_e32 v0, s4
	s_waitcnt vmcnt(0) expcnt(0) lgkmcnt(0)
	ds_read_b32 v2, v0
	s_add_i32 s4, 0, 0x20044
	v_mov_b32_e32 v0, s4
	ds_read_b32 v0, v0
	s_waitcnt lgkmcnt(1)
	v_cmp_ne_u32_e32 vcc, 0, v2
	s_cbranch_vccnz .LBB0_1519
	v_readlane_b32 s4, v255, 0
	s_mul_i32 s16, s35, s4
	s_add_u32 s4, s30, 0xfc00200
	s_addc_u32 s5, s31, 0
	s_add_u32 s6, s30, 0xfc00400
	s_addc_u32 s7, s31, 0
	s_add_u32 s8, s30, 0xfc00500
	s_addc_u32 s9, s31, 0
	s_add_u32 s12, s30, 0xfc00600
	s_addc_u32 s13, s31, 0
	s_add_u32 s14, s30, 0xfc00700
	s_addc_u32 s15, s31, 0
	s_add_u32 s18, s30, 0xfc00800
	s_addc_u32 s19, s31, 0
	s_add_u32 s20, s30, 0xfc00900
	s_addc_u32 s21, s31, 0
	s_add_u32 s24, s30, 0xfc00a00
	s_addc_u32 s25, s31, 0
	s_add_u32 s26, s30, 0xfc00b00
	s_addc_u32 s27, s31, 0
	s_add_u32 s42, s30, 0xfc00c00
	s_addc_u32 s43, s31, 0
	s_add_u32 s44, s30, 0xfc00d00
	s_addc_u32 s45, s31, 0
	s_add_u32 s46, s30, 0xfc00e00
	s_addc_u32 s47, s31, 0
	s_add_u32 s48, s30, 0xfc00f00
	s_addc_u32 s49, s31, 0
	s_add_u32 s50, s30, 0xfc01000
	s_addc_u32 s51, s31, 0
	s_add_u32 s52, s30, 0xfc01100
	s_addc_u32 s53, s31, 0
	s_add_u32 s54, s30, 0xfc01200
	s_addc_u32 s55, s31, 0
	s_add_u32 s56, s30, 0xfc01300
	s_mul_i32 s16, s16, s34
	s_addc_u32 s57, s31, 0
	s_mov_b32 s17, 1
	v_mov_b32_e32 v16, 0
	s_branch .LBB0_1507

.LBB0_1599:
	s_cmp_gt_i32 s69, 8
	s_cselect_b64 s[2:3], -1, 0
	s_and_b64 s[0:1], s[0:1], s[2:3]
	v_readlane_b32 s60, v255, 20
	s_andn2_b64 vcc, exec, s[0:1]
	v_readlane_b32 s61, v255, 21
	s_cbranch_vccnz .LBB0_1653
	s_waitcnt vmcnt(0)
	s_waitcnt vmcnt(0) lgkmcnt(0)
	s_barrier
	v_mov_b32_e32 v0, 0x20040
	ds_read_b32 v2, v0
	ds_read_b32 v3, v0 offset:16
	ds_read_b32 v5, v0 offset:8
	s_lshl_b32 s4, s33, 7
	s_add_u32 s4, s4, 0x3600
	v_lshl_add_u32 v0, v199, 2, s4
	v_mov_b32_e32 v6, 5
	s_waitcnt lgkmcnt(0)
	v_cmp_eq_u32_e32 vcc, 0, v3
	s_cbranch_vccnz .Lxl_orig_7
	v_cmp_lt_u32_e32 vcc, 32, v2
	s_cbranch_vccnz .Lxl_orig_7
	v_lshl_add_u32 v1, v5, 2, s4
	v_cmp_lt_u32_e32 vcc, v199, v2
	s_and_saveexec_b64 s[0:1], vcc
	s_cbranch_execz .LBB0_1652
	v_cmp_eq_u32_e32 vcc, 0, v199
	s_and_saveexec_b64 s[4:5], vcc
	global_store_dword v1, v6, s[92:93]
	s_mov_b64 exec, s[4:5]
	buffer_inv sc1
	s_mov_b32 s4, 0x20000
.Lxl_poll_7:
	global_load_dword v4, v0, s[92:93] sc1
	s_waitcnt vmcnt(0)
	v_cmp_gt_u32_e32 vcc, 5, v4
	s_cbranch_vccz .LBB0_1652
	s_sleep 1
	s_sub_u32 s4, s4, 1
	s_cmp_lg_u32 s4, 0
	s_cbranch_scc1 .Lxl_poll_7
	s_branch .LBB0_1652
.Lxl_orig_7:
	s_mov_b64 s[0:1], exec
	v_readlane_b32 s4, v255, 1
	v_readlane_b32 s5, v255, 2
	s_and_b64 s[4:5], s[0:1], s[4:5]
	s_mov_b64 exec, s[4:5]
	s_cbranch_execz .LBB0_1652
	s_add_i32 s4, 0, 0x20040
	v_mov_b32_e32 v0, s4
	s_waitcnt vmcnt(0) expcnt(0) lgkmcnt(0)
	ds_read_b32 v2, v0
	s_add_i32 s4, 0, 0x20044
	v_mov_b32_e32 v0, s4
	ds_read_b32 v0, v0
	s_waitcnt lgkmcnt(1)
	v_cmp_ne_u32_e32 vcc, 0, v2
	s_cbranch_vccnz .LBB0_1616
	v_readlane_b32 s4, v255, 0
	s_mul_i32 s16, s35, s4
	s_add_u32 s4, s30, 0xfc00200
	s_addc_u32 s5, s31, 0
	s_add_u32 s6, s30, 0xfc00400
	s_addc_u32 s7, s31, 0
	s_add_u32 s8, s30, 0xfc00500
	s_addc_u32 s9, s31, 0
	s_add_u32 s12, s30, 0xfc00600
	s_addc_u32 s13, s31, 0
	s_add_u32 s14, s30, 0xfc00700
	s_addc_u32 s15, s31, 0
	s_add_u32 s18, s30, 0xfc00800
	s_addc_u32 s19, s31, 0
	s_add_u32 s20, s30, 0xfc00900
	s_addc_u32 s21, s31, 0
	s_add_u32 s22, s30, 0xfc00a00
	s_addc_u32 s23, s31, 0
	s_add_u32 s24, s30, 0xfc00b00
	s_addc_u32 s25, s31, 0
	s_add_u32 s26, s30, 0xfc00c00
	s_addc_u32 s27, s31, 0
	s_add_u32 s42, s30, 0xfc00d00
	s_addc_u32 s43, s31, 0
	s_add_u32 s44, s30, 0xfc00e00
	s_addc_u32 s45, s31, 0
	s_add_u32 s46, s30, 0xfc00f00
	s_addc_u32 s47, s31, 0
	s_add_u32 s48, s30, 0xfc01000
	s_addc_u32 s49, s31, 0
	s_add_u32 s50, s30, 0xfc01100
	s_addc_u32 s51, s31, 0
	s_add_u32 s52, s30, 0xfc01200
	s_addc_u32 s53, s31, 0
	s_add_u32 s54, s30, 0xfc01300
	s_mul_i32 s16, s16, s34
	s_addc_u32 s55, s31, 0
	s_mov_b32 s17, 1
	v_mov_b32_e32 v16, 0
	s_branch .LBB0_1604

.LBB0_1710:
	s_cmp_gt_i32 s69, 9
	s_cselect_b64 s[0:1], -1, 0
	s_and_b64 s[2:3], s[6:7], s[0:1]
	s_andn2_b64 vcc, exec, s[2:3]
	s_cbranch_vccnz .LBB0_1764
	s_waitcnt vmcnt(0)
	s_waitcnt vmcnt(0) lgkmcnt(0)
	s_barrier
	v_mov_b32_e32 v0, 0x20040
	ds_read_b32 v2, v0
	ds_read_b32 v3, v0 offset:16
	ds_read_b32 v5, v0 offset:8
	s_lshl_b32 s4, s33, 7
	s_add_u32 s4, s4, 0x3600
	v_lshl_add_u32 v0, v199, 2, s4
	v_mov_b32_e32 v6, 6
	s_waitcnt lgkmcnt(0)
	v_cmp_eq_u32_e32 vcc, 0, v3
	s_cbranch_vccnz .Lxl_orig_8
	v_cmp_lt_u32_e32 vcc, 32, v2
	s_cbranch_vccnz .Lxl_orig_8
	v_lshl_add_u32 v1, v5, 2, s4
	v_cmp_lt_u32_e32 vcc, v199, v2
	s_and_saveexec_b64 s[2:3], vcc
	s_cbranch_execz .LBB0_1763
	v_cmp_eq_u32_e32 vcc, 0, v199
	s_and_saveexec_b64 s[4:5], vcc
	global_store_dword v1, v6, s[92:93]
	s_mov_b64 exec, s[4:5]
	buffer_inv sc1
	s_mov_b32 s4, 0x20000
.Lxl_poll_8:
	global_load_dword v4, v0, s[92:93] sc1
	s_waitcnt vmcnt(0)
	v_cmp_gt_u32_e32 vcc, 6, v4
	s_cbranch_vccz .LBB0_1763
	s_sleep 1
	s_sub_u32 s4, s4, 1
	s_cmp_lg_u32 s4, 0
	s_cbranch_scc1 .Lxl_poll_8
	s_branch .LBB0_1763
